# adds GEMM1 rope-epilogue table prefetch (11-deep, counted waits that no longer wait on store acks) on top of tilebyte+P0
# baseline (speedup 1.0000x reference)
; __device__ __forceinline__ unsigned cvt_pk_bf16(float lo, float hi) { unsigned r; asm volatile("v_cvt_pk_bf16_f32 %0, %1, %2" : "=v"(r) : "v"(lo), "v"(hi)); return r; }
;     __device__ __forceinline__ void operator()(f32x4 (&acc)[2][2][4][2], const pg8::Unit& u, int wr, int wc, int fr, int fq) const {
;     ...
;         if (rope) {
;             const float sc = ((pn < 4) ? SC_QA : (pn >= 9 && pn < 15) ? SC_QB : 1.0f) * ascale;
; #pragma unroll
;             for (int ai = 0; ai < 2; ++ai)
; #pragma unroll
;                 for (int m = 0; m < 4; ++m) {
;                     const int row = row0 + ai * 128 + m * 16;
;                     const f32x4* cp = (md == 1) ? (const f32x4*)(csA + (size_t)row * 32 + 8 * fq) : (const f32x4*)(csB + (size_t)row * 64 + 32 * (wc & 1) + 8 * fq);
;                     const f32x4 t0 = cp[0], t1 = cp[1], t2 = cp[2], t3 = cp[3];
;                     const f32x4 a0 = acc[ai][0][m][0], a1 = acc[ai][0][m][1], b0 = acc[ai][1][m][0], b1 = acc[ai][1][m][1];
;                     u32x4 w0, w1;
;                     w0.x = cvt_pk_bf16((a0[0] * t0[0] - b0[0] * t0[1]) * sc, (a0[1] * t0[2] - b0[1] * t0[3]) * sc);
;                     w0.y = cvt_pk_bf16((a0[2] * t1[0] - b0[2] * t1[1]) * sc, (a0[3] * t1[2] - b0[3] * t1[3]) * sc);
;                     w0.z = cvt_pk_bf16((a1[0] * t2[0] - b1[0] * t2[1]) * sc, (a1[1] * t2[2] - b1[1] * t2[3]) * sc);
;                     w0.w = cvt_pk_bf16((a1[2] * t3[0] - b1[2] * t3[1]) * sc, (a1[3] * t3[2] - b1[3] * t3[3]) * sc);
;                     w1.x = cvt_pk_bf16((b0[0] * t0[0] + a0[0] * t0[1]) * sc, (b0[1] * t0[2] + a0[1] * t0[3]) * sc);
;                     w1.y = cvt_pk_bf16((b0[2] * t1[0] + a0[2] * t1[1]) * sc, (b0[3] * t1[2] + a0[3] * t1[3]) * sc);
;                     w1.z = cvt_pk_bf16((b1[0] * t2[0] + a1[0] * t2[1]) * sc, (b1[1] * t2[2] + a1[1] * t2[3]) * sc);
;                     w1.w = cvt_pk_bf16((b1[2] * t3[0] + a1[2] * t3[1]) * sc, (b1[3] * t3[2] + a1[3] * t3[3]) * sc);
;                     bf16_t* rp = H + (size_t)row * DIN + col0;
;                     *(u32x4*)(rp) = w0; *(u32x4*)(rp + cstep) = w1;
;                     if (m == 3) asm volatile("" ::: "memory");
;                 }
.LBB0_219:
	v_mov_b32_e32 v254, s12
	v_mov_b32_e32 v255, s13
	v_mov_b32_e32 v240, s28
	v_mov_b32_e32 v241, s29
	v_cndmask_b32_e64 v254, v254, v240, s[6:7]
	v_cndmask_b32_e64 v255, v255, v241, s[6:7]
	v_mov_b32_e32 v253, 0
	v_mov_b32_e32 v234, v16
	v_mov_b32_e32 v252, v234
	v_lshlrev_b32_e32 v240, 9, v252
	v_lshlrev_b32_e32 v252, 8, v252
	v_cndmask_b32_e64 v252, v252, v240, s[6:7]
	v_add_u32_e32 v252, v252, v182
	v_lshl_add_u64 v[240:241], v[254:255], 0, v[252:253]
	global_load_dwordx4 v[200:203], v[240:241], off
	global_load_dwordx4 v[204:207], v[240:241], off offset:16
	global_load_dwordx4 v[208:211], v[240:241], off offset:32
	global_load_dwordx4 v[212:215], v[240:241], off offset:48
	v_add_u32_e32 v252, 16, v234
	v_lshlrev_b32_e32 v240, 9, v252
	v_lshlrev_b32_e32 v252, 8, v252
	v_cndmask_b32_e64 v252, v252, v240, s[6:7]
	v_add_u32_e32 v252, v252, v182
	v_lshl_add_u64 v[240:241], v[254:255], 0, v[252:253]
	global_load_dwordx4 v[216:219], v[240:241], off
	global_load_dwordx4 v[220:223], v[240:241], off offset:16
	global_load_dwordx4 v[224:227], v[240:241], off offset:32
	global_load_dwordx4 v[228:231], v[240:241], off offset:48
	v_add_u32_e32 v252, 32, v234
	v_lshlrev_b32_e32 v240, 9, v252
	v_lshlrev_b32_e32 v252, 8, v252
	v_cndmask_b32_e64 v252, v252, v240, s[6:7]
	v_add_u32_e32 v252, v252, v182
	v_lshl_add_u64 v[240:241], v[254:255], 0, v[252:253]
	global_load_dwordx4 v[236:239], v[240:241], off
	global_load_dwordx4 v[244:247], v[240:241], off offset:16
	global_load_dwordx4 v[248:251], v[240:241], off offset:32
	v_ashrrev_i32_e32 v17, 31, v16
	v_lshlrev_b64 v[0:1], 9, v[16:17]
	v_lshlrev_b64 v[2:3], 8, v[16:17]
	v_lshl_add_u64 v[0:1], s[28:29], 0, v[0:1]
	v_lshl_add_u64 v[2:3], s[12:13], 0, v[2:3]
	v_cndmask_b32_e64 v1, v3, v1, s[6:7]
	v_cndmask_b32_e64 v0, v2, v0, s[6:7]
	v_mov_b32_e32 v183, v175
	v_lshl_add_u64 v[4:5], v[0:1], 0, v[182:183]
	s_cmp_lt_u32 s35, 6
	v_mov_b32_e32 v14, v156
	v_mov_b32_e32 v15, v152
	v_mov_b32_e32 v22, v157
	v_mov_b32_e32 v23, v153
	v_mov_b32_e32 v24, v158
	v_mov_b32_e32 v25, v154
	v_mov_b32_e32 v26, v159
	v_mov_b32_e32 v27, v155
	v_mov_b32_e32 v28, v148
	v_mov_b32_e32 v29, v144
	v_mov_b32_e32 v188, v152
	v_mov_b32_e32 v189, v156
	s_cselect_b64 vcc, -1, 0
	v_mov_b32_e32 v30, v149
	v_mov_b32_e32 v31, v145
	v_mov_b32_e32 v184, v150
	v_mov_b32_e32 v185, v146
	v_mov_b32_e32 v186, v151
	v_mov_b32_e32 v187, v147
	v_mov_b32_e32 v156, v153
	v_mov_b32_e32 v152, v154
	v_mov_b32_e32 v153, v158
	v_mov_b32_e32 v158, v155
	v_mov_b32_e32 v154, v144
	v_mov_b32_e32 v155, v148
	v_mov_b32_e32 v148, v145
	v_cndmask_b32_e32 v4, v196, v197, vcc
	v_cndmask_b32_e64 v4, v4, v198, s[8:9]
	s_lshl_b32 s16, s33, 1
	s_waitcnt vmcnt(10)
	v_pk_mul_f32 v[14:15], v[14:15], v[200:201]
	v_pk_mul_f32 v[22:23], v[22:23], v[202:203]
	s_waitcnt vmcnt(9)
	v_pk_mul_f32 v[24:25], v[24:25], v[204:205]
	v_pk_mul_f32 v[26:27], v[26:27], v[206:207]
	s_waitcnt vmcnt(8)
	v_pk_mul_f32 v[28:29], v[28:29], v[208:209]
	v_pk_mul_f32 v[0:1], v[188:189], v[200:201]
	v_pk_mul_f32 v[30:31], v[30:31], v[210:211]
	s_waitcnt vmcnt(7)
	v_pk_mul_f32 v[144:145], v[184:185], v[212:213]
	v_pk_mul_f32 v[184:185], v[186:187], v[214:215]
	v_pk_mul_f32 v[2:3], v[156:157], v[202:203]
	global_load_dwordx4 v[200:203], v[240:241], off offset:48
	v_pk_mul_f32 v[6:7], v[152:153], v[204:205]
	v_pk_mul_f32 v[8:9], v[158:159], v[206:207]
	v_add_u32_e32 v252, 48, v234
	v_lshlrev_b32_e32 v240, 9, v252
	v_lshlrev_b32_e32 v252, 8, v252
	v_cndmask_b32_e64 v252, v252, v240, s[6:7]
	v_add_u32_e32 v252, v252, v182
	v_lshl_add_u64 v[240:241], v[254:255], 0, v[252:253]
	global_load_dwordx4 v[204:207], v[240:241], off
	v_pk_mul_f32 v[10:11], v[154:155], v[208:209]
	v_pk_mul_f32 v[12:13], v[148:149], v[210:211]
	global_load_dwordx4 v[208:211], v[240:241], off offset:16
	v_sub_f32_e32 v5, v14, v15
	v_sub_f32_e32 v14, v22, v23
	v_sub_f32_e32 v15, v24, v25
	v_sub_f32_e32 v17, v26, v27
	v_sub_f32_e32 v22, v28, v29
	v_add_f32_e32 v0, v1, v0
	v_sub_f32_e32 v23, v30, v31
	v_sub_f32_e32 v24, v144, v145
	v_sub_f32_e32 v25, v184, v185
	v_add_f32_e32 v1, v3, v2
	v_add_f32_e32 v2, v7, v6
	v_add_f32_e32 v3, v9, v8
	v_add_f32_e32 v6, v11, v10
	v_add_f32_e32 v12, v13, v12
	v_mul_f32_e32 v7, v4, v14
	v_mul_f32_e32 v8, v4, v15
	v_mul_f32_e32 v9, v4, v17
	v_mul_f32_e32 v10, v4, v22
	v_mul_f32_e32 v0, v4, v0
	v_mul_f32_e32 v5, v4, v5
	v_mul_f32_e32 v11, v4, v23
	v_mul_f32_e32 v13, v4, v24
	v_mul_f32_e32 v14, v4, v25
	v_mul_f32_e32 v1, v4, v1
	v_mul_f32_e32 v15, v4, v6
	v_cvt_pk_bf16_f32 v6, v5, v7
	v_cvt_pk_bf16_f32 v7, v8, v9
	v_cvt_pk_bf16_f32 v8, v10, v11
	v_cvt_pk_bf16_f32 v9, v13, v14
	v_cvt_pk_bf16_f32 v10, v0, v1
	v_mul_f32_e32 v0, v4, v12
	v_mul_f32_e32 v2, v4, v2
	v_mul_f32_e32 v3, v4, v3
	v_cvt_pk_bf16_f32 v11, v2, v3
	v_cvt_pk_bf16_f32 v12, v15, v0
	v_mov_b32_e32 v0, v146
	v_mov_b32_e32 v1, v150
	v_pk_mul_f32 v[0:1], v[0:1], v[212:213]
	v_mov_b32_e32 v150, v147
	v_add_f32_e32 v0, v1, v0
	v_mul_f32_e32 v2, v4, v0
	v_pk_mul_f32 v[0:1], v[150:151], v[214:215]
	global_load_dwordx4 v[212:215], v[240:241], off offset:32
	v_mov_b32_e32 v26, v140
	v_add_f32_e32 v0, v1, v0
	v_mul_f32_e32 v0, v4, v0
	v_cvt_pk_bf16_f32 v13, v2, v0
	v_mov_b64_e32 v[0:1], s[96:97]
	v_mad_i64_i32 v[14:15], s[0:1], v16, s66, v[0:1]
	v_lshlrev_b64 v[2:3], 1, v[174:175]
	v_lshl_add_u64 v[14:15], v[14:15], 0, v[2:3]
	global_store_dwordx4 v[14:15], v[6:9], off
	v_mov_b32_e32 v27, v132
	v_mov_b32_e32 v28, v141
	v_lshl_add_u64 v[6:7], v[14:15], 0, s[16:17]
	v_or_b32_e32 v14, 16, v16
	v_ashrrev_i32_e32 v15, 31, v14
	global_store_dwordx4 v[6:7], v[10:13], off
	v_lshlrev_b64 v[6:7], 9, v[14:15]
	v_lshlrev_b64 v[8:9], 8, v[14:15]
	v_lshl_add_u64 v[6:7], s[28:29], 0, v[6:7]
	v_lshl_add_u64 v[8:9], s[12:13], 0, v[8:9]
	v_cndmask_b32_e64 v7, v9, v7, s[6:7]
	v_cndmask_b32_e64 v6, v8, v6, s[6:7]
	v_lshl_add_u64 v[22:23], v[6:7], 0, v[182:183]
	s_nop 0
	v_mov_b32_e32 v29, v133
	v_mov_b32_e32 v30, v142
	v_mov_b32_e32 v31, v134
	v_mov_b32_e32 v144, v143
	v_mov_b32_e32 v145, v135
	v_mov_b32_e32 v146, v136
	v_mov_b32_e32 v147, v128
	v_mov_b32_e32 v148, v137
	v_mov_b32_e32 v149, v129
	v_mov_b32_e32 v150, v138
	v_mov_b32_e32 v151, v130
	v_mov_b32_e32 v152, v139
	v_mov_b32_e32 v153, v131
	v_mov_b32_e32 v154, v132
	v_mov_b32_e32 v155, v140
	v_mov_b32_e32 v140, v133
	s_waitcnt vmcnt(12)
; __device__ __forceinline__ unsigned cvt_pk_bf16(float lo, float hi) { unsigned r; asm volatile("v_cvt_pk_bf16_f32 %0, %1, %2" : "=v"(r) : "v"(lo), "v"(hi)); return r; }
;     __device__ __forceinline__ void operator()(f32x4 (&acc)[2][2][4][2], const pg8::Unit& u, int wr, int wc, int fr, int fq) const {
;     ...
;         if (rope) {
;             const float sc = ((pn < 4) ? SC_QA : (pn >= 9 && pn < 15) ? SC_QB : 1.0f) * ascale;
; #pragma unroll
;             for (int ai = 0; ai < 2; ++ai)
; #pragma unroll
;                 for (int m = 0; m < 4; ++m) {
;                     const int row = row0 + ai * 128 + m * 16;
;                     const f32x4* cp = (md == 1) ? (const f32x4*)(csA + (size_t)row * 32 + 8 * fq) : (const f32x4*)(csB + (size_t)row * 64 + 32 * (wc & 1) + 8 * fq);
;                     const f32x4 t0 = cp[0], t1 = cp[1], t2 = cp[2], t3 = cp[3];
;                     const f32x4 a0 = acc[ai][0][m][0], a1 = acc[ai][0][m][1], b0 = acc[ai][1][m][0], b1 = acc[ai][1][m][1];
;                     u32x4 w0, w1;
;                     w0.x = cvt_pk_bf16((a0[0] * t0[0] - b0[0] * t0[1]) * sc, (a0[1] * t0[2] - b0[1] * t0[3]) * sc);
;                     w0.y = cvt_pk_bf16((a0[2] * t1[0] - b0[2] * t1[1]) * sc, (a0[3] * t1[2] - b0[3] * t1[3]) * sc);
;                     w0.z = cvt_pk_bf16((a1[0] * t2[0] - b1[0] * t2[1]) * sc, (a1[1] * t2[2] - b1[1] * t2[3]) * sc);
;                     w0.w = cvt_pk_bf16((a1[2] * t3[0] - b1[2] * t3[1]) * sc, (a1[3] * t3[2] - b1[3] * t3[3]) * sc);
;                     w1.x = cvt_pk_bf16((b0[0] * t0[0] + a0[0] * t0[1]) * sc, (b0[1] * t0[2] + a0[1] * t0[3]) * sc);
;                     w1.y = cvt_pk_bf16((b0[2] * t1[0] + a0[2] * t1[1]) * sc, (b0[3] * t1[2] + a0[3] * t1[3]) * sc);
;                     w1.z = cvt_pk_bf16((b1[0] * t2[0] + a1[0] * t2[1]) * sc, (b1[1] * t2[2] + a1[1] * t2[3]) * sc);
;                     w1.w = cvt_pk_bf16((b1[2] * t3[0] + a1[2] * t3[1]) * sc, (b1[3] * t3[2] + a1[3] * t3[3]) * sc);
;                     bf16_t* rp = H + (size_t)row * DIN + col0;
;                     *(u32x4*)(rp) = w0; *(u32x4*)(rp + cstep) = w1;
;                     if (m == 3) asm volatile("" ::: "memory");
;                 }
	v_pk_mul_f32 v[26:27], v[26:27], v[216:217]
	v_pk_mul_f32 v[28:29], v[28:29], v[218:219]
	s_waitcnt vmcnt(11)
	v_pk_mul_f32 v[30:31], v[30:31], v[220:221]
	v_pk_mul_f32 v[132:133], v[144:145], v[222:223]
	s_waitcnt vmcnt(10)
	v_pk_mul_f32 v[144:145], v[146:147], v[224:225]
	v_pk_mul_f32 v[146:147], v[148:149], v[226:227]
	s_waitcnt vmcnt(9)
	v_pk_mul_f32 v[148:149], v[150:151], v[228:229]
	v_pk_mul_f32 v[150:151], v[152:153], v[230:231]
	v_pk_mul_f32 v[6:7], v[154:155], v[216:217]
	v_sub_f32_e32 v5, v26, v27
	v_pk_mul_f32 v[140:141], v[140:141], v[218:219]
	global_load_dwordx4 v[216:219], v[240:241], off offset:48
	v_sub_f32_e32 v8, v28, v29
	v_sub_f32_e32 v9, v30, v31
	v_sub_f32_e32 v15, v132, v133
	v_sub_f32_e32 v17, v144, v145
	v_sub_f32_e32 v26, v146, v147
	v_sub_f32_e32 v27, v148, v149
	v_sub_f32_e32 v28, v150, v151
	v_add_f32_e32 v6, v7, v6
	v_mul_f32_e32 v5, v4, v5
	v_mul_f32_e32 v7, v4, v8
	v_mul_f32_e32 v8, v4, v9
	v_mul_f32_e32 v9, v4, v15
	v_mul_f32_e32 v15, v4, v17
	v_mul_f32_e32 v17, v4, v26
	v_mul_f32_e32 v26, v4, v27
	v_mul_f32_e32 v27, v4, v28
	v_mul_f32_e32 v28, v4, v6
	v_cvt_pk_bf16_f32 v6, v5, v7
	v_add_f32_e32 v5, v141, v140
	v_cvt_pk_bf16_f32 v7, v8, v9
	v_cvt_pk_bf16_f32 v8, v15, v17
	v_cvt_pk_bf16_f32 v9, v26, v27
	v_mul_f32_e32 v5, v4, v5
	v_cvt_pk_bf16_f32 v26, v28, v5
	v_mov_b32_e32 v28, v134
	v_mov_b32_e32 v29, v142
	v_pk_mul_f32 v[10:11], v[28:29], v[220:221]
	v_mov_b32_e32 v142, v135
	v_add_f32_e32 v5, v11, v10
	v_pk_mul_f32 v[10:11], v[142:143], v[222:223]
	v_add_u32_e32 v252, 128, v234
	v_lshlrev_b32_e32 v240, 9, v252
	v_lshlrev_b32_e32 v252, 8, v252
	v_cndmask_b32_e64 v252, v252, v240, s[6:7]
	v_add_u32_e32 v252, v252, v182
	v_lshl_add_u64 v[240:241], v[254:255], 0, v[252:253]
	global_load_dwordx4 v[220:223], v[240:241], off
	v_mul_f32_e32 v5, v4, v5
	v_add_f32_e32 v10, v11, v10
	v_mul_f32_e32 v10, v4, v10
	v_cvt_pk_bf16_f32 v27, v5, v10
	v_mov_b32_e32 v10, v128
	v_mov_b32_e32 v11, v136
	v_pk_mul_f32 v[10:11], v[10:11], v[224:225]
	v_mov_b32_e32 v136, v129
	v_add_f32_e32 v5, v11, v10
	v_pk_mul_f32 v[10:11], v[136:137], v[226:227]
	global_load_dwordx4 v[224:227], v[240:241], off offset:16
	v_mul_f32_e32 v5, v4, v5
	v_add_f32_e32 v10, v11, v10
	v_mul_f32_e32 v10, v4, v10
	v_cvt_pk_bf16_f32 v28, v5, v10
	v_mov_b32_e32 v10, v130
	v_mov_b32_e32 v11, v138
	v_pk_mul_f32 v[10:11], v[10:11], v[228:229]
	v_mov_b32_e32 v138, v131
	v_add_f32_e32 v5, v11, v10
	v_pk_mul_f32 v[10:11], v[138:139], v[230:231]
	global_load_dwordx4 v[228:231], v[240:241], off offset:32
	v_mul_f32_e32 v5, v4, v5
	v_add_f32_e32 v10, v11, v10
	v_mul_f32_e32 v10, v4, v10
	v_cvt_pk_bf16_f32 v29, v5, v10
	v_mad_i64_i32 v[10:11], s[0:1], v14, s66, v[0:1]
	v_lshl_add_u64 v[10:11], v[10:11], 0, v[2:3]
	v_or_b32_e32 v14, 32, v16
	global_store_dwordx4 v[10:11], v[6:9], off
	v_ashrrev_i32_e32 v15, 31, v14
	v_mov_b32_e32 v130, v120
	v_lshl_add_u64 v[6:7], v[10:11], 0, s[16:17]
	global_store_dwordx4 v[6:7], v[26:29], off
	v_lshlrev_b64 v[6:7], 9, v[14:15]
	v_lshlrev_b64 v[8:9], 8, v[14:15]
	v_lshl_add_u64 v[6:7], s[28:29], 0, v[6:7]
	v_lshl_add_u64 v[8:9], s[12:13], 0, v[8:9]
	v_cndmask_b32_e64 v7, v9, v7, s[6:7]
	v_cndmask_b32_e64 v6, v8, v6, s[6:7]
	v_lshl_add_u64 v[22:23], v[6:7], 0, v[182:183]
	s_nop 0
	v_mov_b32_e32 v26, v124
	v_mov_b32_e32 v27, v116
	v_mov_b32_e32 v28, v125
	v_mov_b32_e32 v29, v117
	v_mov_b32_e32 v131, v112
	v_mov_b32_e32 v132, v121
	v_mov_b32_e32 v133, v113
	v_mov_b32_e32 v30, v126
	v_mov_b32_e32 v31, v118
	v_mov_b32_e32 v128, v127
	v_mov_b32_e32 v129, v119
	s_waitcnt vmcnt(14)
	v_pk_mul_f32 v[26:27], v[26:27], v[236:237]
	v_pk_mul_f32 v[28:29], v[28:29], v[238:239]
	s_waitcnt vmcnt(12)
	v_pk_mul_f32 v[130:131], v[130:131], v[248:249]
	v_pk_mul_f32 v[132:133], v[132:133], v[250:251]
	v_pk_mul_f32 v[30:31], v[30:31], v[244:245]
	v_pk_mul_f32 v[128:129], v[128:129], v[246:247]
	v_sub_f32_e32 v5, v26, v27
	v_sub_f32_e32 v15, v28, v29
	v_sub_f32_e32 v27, v130, v131
	v_sub_f32_e32 v28, v132, v133
	v_sub_f32_e32 v17, v30, v31
	v_sub_f32_e32 v26, v128, v129
	v_mul_f32_e32 v30, v4, v27
	v_mul_f32_e32 v28, v4, v28
	v_mul_f32_e32 v5, v4, v5
	v_mul_f32_e32 v15, v4, v15
	v_mul_f32_e32 v17, v4, v17
	v_mul_f32_e32 v29, v4, v26
	v_cvt_pk_bf16_f32 v26, v5, v15
	v_cvt_pk_bf16_f32 v27, v17, v29
	v_cvt_pk_bf16_f32 v28, v30, v28
	v_mov_b32_e32 v30, v122
	v_mov_b32_e32 v31, v114
	s_waitcnt vmcnt(11)
; __device__ __forceinline__ unsigned cvt_pk_bf16(float lo, float hi) { unsigned r; asm volatile("v_cvt_pk_bf16_f32 %0, %1, %2" : "=v"(r) : "v"(lo), "v"(hi)); return r; }
;     __device__ __forceinline__ void operator()(f32x4 (&acc)[2][2][4][2], const pg8::Unit& u, int wr, int wc, int fr, int fq) const {
;     ...
;         if (rope) {
;             const float sc = ((pn < 4) ? SC_QA : (pn >= 9 && pn < 15) ? SC_QB : 1.0f) * ascale;
; #pragma unroll
;             for (int ai = 0; ai < 2; ++ai)
; #pragma unroll
;                 for (int m = 0; m < 4; ++m) {
;                     const int row = row0 + ai * 128 + m * 16;
;                     const f32x4* cp = (md == 1) ? (const f32x4*)(csA + (size_t)row * 32 + 8 * fq) : (const f32x4*)(csB + (size_t)row * 64 + 32 * (wc & 1) + 8 * fq);
;                     const f32x4 t0 = cp[0], t1 = cp[1], t2 = cp[2], t3 = cp[3];
;                     const f32x4 a0 = acc[ai][0][m][0], a1 = acc[ai][0][m][1], b0 = acc[ai][1][m][0], b1 = acc[ai][1][m][1];
;                     u32x4 w0, w1;
;                     w0.x = cvt_pk_bf16((a0[0] * t0[0] - b0[0] * t0[1]) * sc, (a0[1] * t0[2] - b0[1] * t0[3]) * sc);
;                     w0.y = cvt_pk_bf16((a0[2] * t1[0] - b0[2] * t1[1]) * sc, (a0[3] * t1[2] - b0[3] * t1[3]) * sc);
;                     w0.z = cvt_pk_bf16((a1[0] * t2[0] - b1[0] * t2[1]) * sc, (a1[1] * t2[2] - b1[1] * t2[3]) * sc);
;                     w0.w = cvt_pk_bf16((a1[2] * t3[0] - b1[2] * t3[1]) * sc, (a1[3] * t3[2] - b1[3] * t3[3]) * sc);
;                     w1.x = cvt_pk_bf16((b0[0] * t0[0] + a0[0] * t0[1]) * sc, (b0[1] * t0[2] + a0[1] * t0[3]) * sc);
;                     w1.y = cvt_pk_bf16((b0[2] * t1[0] + a0[2] * t1[1]) * sc, (b0[3] * t1[2] + a0[3] * t1[3]) * sc);
;                     w1.z = cvt_pk_bf16((b1[0] * t2[0] + a1[0] * t2[1]) * sc, (b1[1] * t2[2] + a1[1] * t2[3]) * sc);
;                     w1.w = cvt_pk_bf16((b1[2] * t3[0] + a1[2] * t3[1]) * sc, (b1[3] * t3[2] + a1[3] * t3[3]) * sc);
;                     bf16_t* rp = H + (size_t)row * DIN + col0;
;                     *(u32x4*)(rp) = w0; *(u32x4*)(rp + cstep) = w1;
;                     if (m == 3) asm volatile("" ::: "memory");
;                 }
	v_pk_mul_f32 v[30:31], v[30:31], v[200:201]
	s_nop 0
	v_sub_f32_e32 v5, v30, v31
	v_mov_b32_e32 v30, v123
	v_mov_b32_e32 v31, v115
	v_pk_mul_f32 v[30:31], v[30:31], v[202:203]
	v_mul_f32_e32 v5, v4, v5
	v_sub_f32_e32 v15, v30, v31
	v_mov_b32_e32 v30, v116
	v_mov_b32_e32 v31, v124
	v_pk_mul_f32 v[6:7], v[30:31], v[236:237]
	v_mov_b32_e32 v124, v117
	v_mul_f32_e32 v15, v4, v15
	v_cvt_pk_bf16_f32 v29, v5, v15
	v_add_f32_e32 v5, v7, v6
	v_pk_mul_f32 v[6:7], v[124:125], v[238:239]
	global_load_dwordx4 v[236:239], v[240:241], off offset:48
	v_mov_b32_e32 v8, v118
	v_add_f32_e32 v6, v7, v6
	v_mov_b32_e32 v9, v126
	v_mul_f32_e32 v5, v4, v5
	v_mul_f32_e32 v6, v4, v6
	v_pk_mul_f32 v[8:9], v[8:9], v[244:245]
	v_mov_b32_e32 v126, v119
	v_cvt_pk_bf16_f32 v6, v5, v6
	v_add_f32_e32 v5, v9, v8
	v_pk_mul_f32 v[8:9], v[126:127], v[246:247]
	v_add_u32_e32 v252, 144, v234
	v_lshlrev_b32_e32 v240, 9, v252
	v_lshlrev_b32_e32 v252, 8, v252
	v_cndmask_b32_e64 v252, v252, v240, s[6:7]
	v_add_u32_e32 v252, v252, v182
	v_lshl_add_u64 v[240:241], v[254:255], 0, v[252:253]
	global_load_dwordx4 v[244:247], v[240:241], off
	v_mul_f32_e32 v5, v4, v5
	v_add_f32_e32 v7, v9, v8
	v_mov_b32_e32 v8, v112
	v_mov_b32_e32 v9, v120
	v_mul_f32_e32 v7, v4, v7
	v_pk_mul_f32 v[8:9], v[8:9], v[248:249]
	v_mov_b32_e32 v120, v113
	v_cvt_pk_bf16_f32 v7, v5, v7
	v_add_f32_e32 v5, v9, v8
	v_pk_mul_f32 v[8:9], v[120:121], v[250:251]
	global_load_dwordx4 v[248:251], v[240:241], off offset:16
	v_mov_b32_e32 v10, v114
	v_add_f32_e32 v8, v9, v8
	v_mov_b32_e32 v11, v122
	v_mul_f32_e32 v5, v4, v5
	v_mul_f32_e32 v8, v4, v8
	v_pk_mul_f32 v[10:11], v[10:11], v[200:201]
	v_mov_b32_e32 v122, v115
	v_cvt_pk_bf16_f32 v8, v5, v8
	v_add_f32_e32 v5, v11, v10
	v_pk_mul_f32 v[10:11], v[122:123], v[202:203]
	global_load_dwordx4 v[200:203], v[240:241], off offset:32
	v_mul_f32_e32 v5, v4, v5
	v_add_f32_e32 v9, v11, v10
	v_mad_i64_i32 v[10:11], s[0:1], v14, s66, v[0:1]
	v_mul_f32_e32 v9, v4, v9
	v_lshl_add_u64 v[10:11], v[10:11], 0, v[2:3]
	v_or_b32_e32 v14, 48, v16
	v_cvt_pk_bf16_f32 v9, v5, v9
	global_store_dwordx4 v[10:11], v[26:29], off
	v_lshl_add_u64 v[10:11], v[10:11], 0, s[16:17]
	v_ashrrev_i32_e32 v15, 31, v14
	global_store_dwordx4 v[10:11], v[6:9], off
	v_mov_b32_e32 v28, v109
	v_mov_b32_e32 v29, v101
	v_lshlrev_b64 v[6:7], 9, v[14:15]
	v_lshlrev_b64 v[8:9], 8, v[14:15]
	v_lshl_add_u64 v[6:7], s[28:29], 0, v[6:7]
	v_lshl_add_u64 v[8:9], s[12:13], 0, v[8:9]
	v_cndmask_b32_e64 v7, v9, v7, s[6:7]
	v_cndmask_b32_e64 v6, v8, v6, s[6:7]
	v_lshl_add_u64 v[22:23], v[6:7], 0, v[182:183]
	s_nop 0
	v_mov_b32_e32 v26, v108
	v_mov_b32_e32 v27, v100
	v_mov_b32_e32 v30, v110
	v_mov_b32_e32 v31, v102
	s_waitcnt vmcnt(16)
	v_pk_mul_f32 v[28:29], v[28:29], v[206:207]
	v_pk_mul_f32 v[26:27], v[26:27], v[204:205]
	v_sub_f32_e32 v15, v28, v29
	v_mov_b32_e32 v28, v111
	v_mov_b32_e32 v29, v103
	s_waitcnt vmcnt(15)
	v_pk_mul_f32 v[30:31], v[30:31], v[208:209]
	v_sub_f32_e32 v5, v26, v27
	v_mul_f32_e32 v15, v4, v15
	v_pk_mul_f32 v[28:29], v[28:29], v[210:211]
	v_sub_f32_e32 v17, v30, v31
	v_mul_f32_e32 v5, v4, v5
	v_cvt_pk_bf16_f32 v26, v5, v15
	v_sub_f32_e32 v15, v28, v29
	v_mov_b32_e32 v28, v104
	v_mov_b32_e32 v29, v96
	v_mul_f32_e32 v5, v4, v17
	s_waitcnt vmcnt(14)
	v_pk_mul_f32 v[28:29], v[28:29], v[212:213]
	v_mul_f32_e32 v15, v4, v15
	v_cvt_pk_bf16_f32 v27, v5, v15
	v_sub_f32_e32 v5, v28, v29
	v_mov_b32_e32 v28, v105
	v_mov_b32_e32 v29, v97
	v_pk_mul_f32 v[28:29], v[28:29], v[214:215]
	v_mov_b32_e32 v30, v106
	v_mov_b32_e32 v31, v98
	v_mul_f32_e32 v5, v4, v5
	v_sub_f32_e32 v15, v28, v29
	s_waitcnt vmcnt(11)
	v_pk_mul_f32 v[30:31], v[30:31], v[216:217]
	v_mul_f32_e32 v15, v4, v15
	v_cvt_pk_bf16_f32 v28, v5, v15
	v_sub_f32_e32 v5, v30, v31
	v_mov_b32_e32 v30, v107
	v_mov_b32_e32 v31, v99
	v_pk_mul_f32 v[30:31], v[30:31], v[218:219]
	v_mul_f32_e32 v5, v4, v5
	v_sub_f32_e32 v15, v30, v31
	v_mov_b32_e32 v30, v100
	v_mov_b32_e32 v31, v108
	v_pk_mul_f32 v[6:7], v[30:31], v[204:205]
	v_mov_b32_e32 v108, v101
	v_mul_f32_e32 v15, v4, v15
	v_cvt_pk_bf16_f32 v29, v5, v15
	v_add_f32_e32 v5, v7, v6
	v_pk_mul_f32 v[6:7], v[108:109], v[206:207]
	global_load_dwordx4 v[204:207], v[240:241], off offset:48
	v_mov_b32_e32 v8, v102
	v_add_f32_e32 v6, v7, v6
	v_mov_b32_e32 v9, v110
	v_mul_f32_e32 v5, v4, v5
	v_mul_f32_e32 v6, v4, v6
	v_pk_mul_f32 v[8:9], v[8:9], v[208:209]
	v_mov_b32_e32 v110, v103
	v_cvt_pk_bf16_f32 v6, v5, v6
	v_add_f32_e32 v5, v9, v8
	v_pk_mul_f32 v[8:9], v[110:111], v[210:211]
	v_add_u32_e32 v252, 160, v234
	v_lshlrev_b32_e32 v240, 9, v252
	v_lshlrev_b32_e32 v252, 8, v252
	v_cndmask_b32_e64 v252, v252, v240, s[6:7]
	v_add_u32_e32 v252, v252, v182
	v_lshl_add_u64 v[240:241], v[254:255], 0, v[252:253]
	global_load_dwordx4 v[208:211], v[240:241], off
	v_mul_f32_e32 v5, v4, v5
	v_add_f32_e32 v7, v9, v8
	v_mov_b32_e32 v8, v96
	v_mov_b32_e32 v9, v104
	v_mul_f32_e32 v7, v4, v7
	v_pk_mul_f32 v[8:9], v[8:9], v[212:213]
	v_mov_b32_e32 v104, v97
	v_cvt_pk_bf16_f32 v7, v5, v7
	v_add_f32_e32 v5, v9, v8
	v_pk_mul_f32 v[8:9], v[104:105], v[214:215]
	global_load_dwordx4 v[212:215], v[240:241], off offset:16
	v_mov_b32_e32 v10, v98
	v_add_f32_e32 v8, v9, v8
	v_mov_b32_e32 v11, v106
	v_mul_f32_e32 v5, v4, v5
	v_mul_f32_e32 v8, v4, v8
	v_pk_mul_f32 v[10:11], v[10:11], v[216:217]
	v_mov_b32_e32 v106, v99
	v_cvt_pk_bf16_f32 v8, v5, v8
	v_add_f32_e32 v5, v11, v10
	v_pk_mul_f32 v[10:11], v[106:107], v[218:219]
	global_load_dwordx4 v[216:219], v[240:241], off offset:32
	v_mul_f32_e32 v5, v4, v5
	v_add_f32_e32 v9, v11, v10
	v_mad_i64_i32 v[10:11], s[0:1], v14, s66, v[0:1]
	v_mul_f32_e32 v9, v4, v9
	v_lshl_add_u64 v[10:11], v[10:11], 0, v[2:3]
	v_add_u32_e32 v14, 0x80, v16
	v_cvt_pk_bf16_f32 v9, v5, v9
	global_store_dwordx4 v[10:11], v[26:29], off
	v_lshl_add_u64 v[10:11], v[10:11], 0, s[16:17]
	v_ashrrev_i32_e32 v15, 31, v14
	global_store_dwordx4 v[10:11], v[6:9], off
	v_mov_b32_e32 v26, v92
	v_mov_b32_e32 v27, v84
	v_lshlrev_b64 v[6:7], 9, v[14:15]
	v_lshlrev_b64 v[8:9], 8, v[14:15]
	v_lshl_add_u64 v[6:7], s[28:29], 0, v[6:7]
	v_lshl_add_u64 v[8:9], s[12:13], 0, v[8:9]
	v_cndmask_b32_e64 v7, v9, v7, s[6:7]
	v_cndmask_b32_e64 v6, v8, v6, s[6:7]
	v_lshl_add_u64 v[22:23], v[6:7], 0, v[182:183]
	s_nop 0
	v_mov_b32_e32 v28, v94
	v_mov_b32_e32 v29, v86
	v_mov_b32_e32 v30, v90
	v_mov_b32_e32 v31, v82
	s_waitcnt vmcnt(16)
; __device__ __forceinline__ unsigned cvt_pk_bf16(float lo, float hi) { unsigned r; asm volatile("v_cvt_pk_bf16_f32 %0, %1, %2" : "=v"(r) : "v"(lo), "v"(hi)); return r; }
;     __device__ __forceinline__ void operator()(f32x4 (&acc)[2][2][4][2], const pg8::Unit& u, int wr, int wc, int fr, int fq) const {
;     ...
;         if (rope) {
;             const float sc = ((pn < 4) ? SC_QA : (pn >= 9 && pn < 15) ? SC_QB : 1.0f) * ascale;
; #pragma unroll
;             for (int ai = 0; ai < 2; ++ai)
; #pragma unroll
;                 for (int m = 0; m < 4; ++m) {
;                     const int row = row0 + ai * 128 + m * 16;
;                     const f32x4* cp = (md == 1) ? (const f32x4*)(csA + (size_t)row * 32 + 8 * fq) : (const f32x4*)(csB + (size_t)row * 64 + 32 * (wc & 1) + 8 * fq);
;                     const f32x4 t0 = cp[0], t1 = cp[1], t2 = cp[2], t3 = cp[3];
;                     const f32x4 a0 = acc[ai][0][m][0], a1 = acc[ai][0][m][1], b0 = acc[ai][1][m][0], b1 = acc[ai][1][m][1];
;                     u32x4 w0, w1;
;                     w0.x = cvt_pk_bf16((a0[0] * t0[0] - b0[0] * t0[1]) * sc, (a0[1] * t0[2] - b0[1] * t0[3]) * sc);
;                     w0.y = cvt_pk_bf16((a0[2] * t1[0] - b0[2] * t1[1]) * sc, (a0[3] * t1[2] - b0[3] * t1[3]) * sc);
;                     w0.z = cvt_pk_bf16((a1[0] * t2[0] - b1[0] * t2[1]) * sc, (a1[1] * t2[2] - b1[1] * t2[3]) * sc);
;                     w0.w = cvt_pk_bf16((a1[2] * t3[0] - b1[2] * t3[1]) * sc, (a1[3] * t3[2] - b1[3] * t3[3]) * sc);
;                     w1.x = cvt_pk_bf16((b0[0] * t0[0] + a0[0] * t0[1]) * sc, (b0[1] * t0[2] + a0[1] * t0[3]) * sc);
;                     w1.y = cvt_pk_bf16((b0[2] * t1[0] + a0[2] * t1[1]) * sc, (b0[3] * t1[2] + a0[3] * t1[3]) * sc);
;                     w1.z = cvt_pk_bf16((b1[0] * t2[0] + a1[0] * t2[1]) * sc, (b1[1] * t2[2] + a1[1] * t2[3]) * sc);
;                     w1.w = cvt_pk_bf16((b1[2] * t3[0] + a1[2] * t3[1]) * sc, (b1[3] * t3[2] + a1[3] * t3[3]) * sc);
;                     bf16_t* rp = H + (size_t)row * DIN + col0;
;                     *(u32x4*)(rp) = w0; *(u32x4*)(rp + cstep) = w1;
;                     if (m == 3) asm volatile("" ::: "memory");
;                 }
	v_pk_mul_f32 v[26:27], v[26:27], v[220:221]
	s_nop 0
	v_sub_f32_e32 v5, v26, v27
	v_mov_b32_e32 v26, v93
	v_mov_b32_e32 v27, v85
	v_pk_mul_f32 v[26:27], v[26:27], v[222:223]
	v_mul_f32_e32 v5, v4, v5
	v_sub_f32_e32 v15, v26, v27
	s_waitcnt vmcnt(15)
	v_pk_mul_f32 v[28:29], v[28:29], v[224:225]
	v_mul_f32_e32 v15, v4, v15
	v_cvt_pk_bf16_f32 v26, v5, v15
	v_sub_f32_e32 v5, v28, v29
	v_mov_b32_e32 v28, v95
	v_mov_b32_e32 v29, v87
	v_pk_mul_f32 v[28:29], v[28:29], v[226:227]
	v_mul_f32_e32 v5, v4, v5
	v_sub_f32_e32 v15, v28, v29
	v_mov_b32_e32 v28, v88
	v_mov_b32_e32 v29, v80
	s_waitcnt vmcnt(14)
	v_pk_mul_f32 v[28:29], v[28:29], v[228:229]
	v_mul_f32_e32 v15, v4, v15
	v_cvt_pk_bf16_f32 v27, v5, v15
	v_sub_f32_e32 v5, v28, v29
	v_mov_b32_e32 v28, v89
	v_mov_b32_e32 v29, v81
	v_pk_mul_f32 v[28:29], v[28:29], v[230:231]
	v_mul_f32_e32 v5, v4, v5
	v_sub_f32_e32 v15, v28, v29
	s_waitcnt vmcnt(11)
	v_pk_mul_f32 v[30:31], v[30:31], v[236:237]
	v_mul_f32_e32 v15, v4, v15
	v_cvt_pk_bf16_f32 v28, v5, v15
	v_sub_f32_e32 v5, v30, v31
	v_mov_b32_e32 v30, v91
	v_mov_b32_e32 v31, v83
	v_pk_mul_f32 v[30:31], v[30:31], v[238:239]
	v_mul_f32_e32 v5, v4, v5
	v_sub_f32_e32 v15, v30, v31
	v_mov_b32_e32 v30, v84
	v_mov_b32_e32 v31, v92
	v_pk_mul_f32 v[6:7], v[30:31], v[220:221]
	v_mov_b32_e32 v92, v85
	v_mul_f32_e32 v15, v4, v15
	v_cvt_pk_bf16_f32 v29, v5, v15
	v_add_f32_e32 v5, v7, v6
	v_pk_mul_f32 v[6:7], v[92:93], v[222:223]
	global_load_dwordx4 v[220:223], v[240:241], off offset:48
	v_mov_b32_e32 v8, v86
	v_add_f32_e32 v6, v7, v6
	v_mov_b32_e32 v9, v94
	v_mul_f32_e32 v5, v4, v5
	v_mul_f32_e32 v6, v4, v6
	v_pk_mul_f32 v[8:9], v[8:9], v[224:225]
	v_mov_b32_e32 v94, v87
	v_cvt_pk_bf16_f32 v6, v5, v6
	v_add_f32_e32 v5, v9, v8
	v_pk_mul_f32 v[8:9], v[94:95], v[226:227]
	v_add_u32_e32 v252, 176, v234
	v_lshlrev_b32_e32 v240, 9, v252
	v_lshlrev_b32_e32 v252, 8, v252
	v_cndmask_b32_e64 v252, v252, v240, s[6:7]
	v_add_u32_e32 v252, v252, v182
	v_lshl_add_u64 v[240:241], v[254:255], 0, v[252:253]
	global_load_dwordx4 v[224:227], v[240:241], off
	v_mul_f32_e32 v5, v4, v5
	v_add_f32_e32 v7, v9, v8
	v_mov_b32_e32 v8, v80
	v_mov_b32_e32 v9, v88
	v_mul_f32_e32 v7, v4, v7
	v_pk_mul_f32 v[8:9], v[8:9], v[228:229]
	v_mov_b32_e32 v88, v81
	v_cvt_pk_bf16_f32 v7, v5, v7
	v_add_f32_e32 v5, v9, v8
	v_pk_mul_f32 v[8:9], v[88:89], v[230:231]
	global_load_dwordx4 v[228:231], v[240:241], off offset:16
	v_mov_b32_e32 v10, v82
	v_add_f32_e32 v8, v9, v8
	v_mov_b32_e32 v11, v90
	v_mul_f32_e32 v5, v4, v5
	v_mul_f32_e32 v8, v4, v8
	v_pk_mul_f32 v[10:11], v[10:11], v[236:237]
	v_mov_b32_e32 v90, v83
	v_cvt_pk_bf16_f32 v8, v5, v8
	v_add_f32_e32 v5, v11, v10
	v_pk_mul_f32 v[10:11], v[90:91], v[238:239]
	global_load_dwordx4 v[236:239], v[240:241], off offset:32
	v_mul_f32_e32 v5, v4, v5
	v_add_f32_e32 v9, v11, v10
	v_mad_i64_i32 v[10:11], s[0:1], v14, s66, v[0:1]
	v_mul_f32_e32 v9, v4, v9
	v_lshl_add_u64 v[10:11], v[10:11], 0, v[2:3]
	v_add_u32_e32 v14, 0x90, v16
	v_cvt_pk_bf16_f32 v9, v5, v9
	global_store_dwordx4 v[10:11], v[26:29], off
	v_lshl_add_u64 v[10:11], v[10:11], 0, s[16:17]
	v_ashrrev_i32_e32 v15, 31, v14
	global_store_dwordx4 v[10:11], v[6:9], off
	v_mov_b32_e32 v26, v76
	v_mov_b32_e32 v27, v68
	v_lshlrev_b64 v[6:7], 9, v[14:15]
	v_lshlrev_b64 v[8:9], 8, v[14:15]
	v_lshl_add_u64 v[6:7], s[28:29], 0, v[6:7]
	v_lshl_add_u64 v[8:9], s[12:13], 0, v[8:9]
	v_cndmask_b32_e64 v7, v9, v7, s[6:7]
	v_cndmask_b32_e64 v6, v8, v6, s[6:7]
	v_lshl_add_u64 v[22:23], v[6:7], 0, v[182:183]
	s_nop 0
	v_mov_b32_e32 v28, v78
	v_mov_b32_e32 v29, v70
	v_mov_b32_e32 v30, v74
	v_mov_b32_e32 v31, v66
	s_waitcnt vmcnt(16)
	v_pk_mul_f32 v[26:27], v[26:27], v[244:245]
	s_nop 0
	v_sub_f32_e32 v5, v26, v27
	v_mov_b32_e32 v26, v77
	v_mov_b32_e32 v27, v69
	v_pk_mul_f32 v[26:27], v[26:27], v[246:247]
	v_mul_f32_e32 v5, v4, v5
	v_sub_f32_e32 v15, v26, v27
	s_waitcnt vmcnt(15)
	v_pk_mul_f32 v[28:29], v[28:29], v[248:249]
	v_mul_f32_e32 v15, v4, v15
	v_cvt_pk_bf16_f32 v26, v5, v15
	v_sub_f32_e32 v5, v28, v29
	v_mov_b32_e32 v28, v79
	v_mov_b32_e32 v29, v71
	v_pk_mul_f32 v[28:29], v[28:29], v[250:251]
	v_mul_f32_e32 v5, v4, v5
	v_sub_f32_e32 v15, v28, v29
	v_mov_b32_e32 v28, v72
	v_mov_b32_e32 v29, v64
	s_waitcnt vmcnt(14)
	v_pk_mul_f32 v[28:29], v[28:29], v[200:201]
	v_mul_f32_e32 v15, v4, v15
	v_cvt_pk_bf16_f32 v27, v5, v15
	v_sub_f32_e32 v5, v28, v29
	v_mov_b32_e32 v28, v73
	v_mov_b32_e32 v29, v65
	v_pk_mul_f32 v[28:29], v[28:29], v[202:203]
	v_mul_f32_e32 v5, v4, v5
	v_sub_f32_e32 v15, v28, v29
	s_waitcnt vmcnt(11)
; __device__ __forceinline__ unsigned cvt_pk_bf16(float lo, float hi) { unsigned r; asm volatile("v_cvt_pk_bf16_f32 %0, %1, %2" : "=v"(r) : "v"(lo), "v"(hi)); return r; }
;     __device__ __forceinline__ void operator()(f32x4 (&acc)[2][2][4][2], const pg8::Unit& u, int wr, int wc, int fr, int fq) const {
;     ...
;         if (rope) {
;             const float sc = ((pn < 4) ? SC_QA : (pn >= 9 && pn < 15) ? SC_QB : 1.0f) * ascale;
; #pragma unroll
;             for (int ai = 0; ai < 2; ++ai)
; #pragma unroll
;                 for (int m = 0; m < 4; ++m) {
;                     const int row = row0 + ai * 128 + m * 16;
;                     const f32x4* cp = (md == 1) ? (const f32x4*)(csA + (size_t)row * 32 + 8 * fq) : (const f32x4*)(csB + (size_t)row * 64 + 32 * (wc & 1) + 8 * fq);
;                     const f32x4 t0 = cp[0], t1 = cp[1], t2 = cp[2], t3 = cp[3];
;                     const f32x4 a0 = acc[ai][0][m][0], a1 = acc[ai][0][m][1], b0 = acc[ai][1][m][0], b1 = acc[ai][1][m][1];
;                     u32x4 w0, w1;
;                     w0.x = cvt_pk_bf16((a0[0] * t0[0] - b0[0] * t0[1]) * sc, (a0[1] * t0[2] - b0[1] * t0[3]) * sc);
;                     w0.y = cvt_pk_bf16((a0[2] * t1[0] - b0[2] * t1[1]) * sc, (a0[3] * t1[2] - b0[3] * t1[3]) * sc);
;                     w0.z = cvt_pk_bf16((a1[0] * t2[0] - b1[0] * t2[1]) * sc, (a1[1] * t2[2] - b1[1] * t2[3]) * sc);
;                     w0.w = cvt_pk_bf16((a1[2] * t3[0] - b1[2] * t3[1]) * sc, (a1[3] * t3[2] - b1[3] * t3[3]) * sc);
;                     w1.x = cvt_pk_bf16((b0[0] * t0[0] + a0[0] * t0[1]) * sc, (b0[1] * t0[2] + a0[1] * t0[3]) * sc);
;                     w1.y = cvt_pk_bf16((b0[2] * t1[0] + a0[2] * t1[1]) * sc, (b0[3] * t1[2] + a0[3] * t1[3]) * sc);
;                     w1.z = cvt_pk_bf16((b1[0] * t2[0] + a1[0] * t2[1]) * sc, (b1[1] * t2[2] + a1[1] * t2[3]) * sc);
;                     w1.w = cvt_pk_bf16((b1[2] * t3[0] + a1[2] * t3[1]) * sc, (b1[3] * t3[2] + a1[3] * t3[3]) * sc);
;                     bf16_t* rp = H + (size_t)row * DIN + col0;
;                     *(u32x4*)(rp) = w0; *(u32x4*)(rp + cstep) = w1;
;                     if (m == 3) asm volatile("" ::: "memory");
;                 }
	v_pk_mul_f32 v[30:31], v[30:31], v[204:205]
	v_mul_f32_e32 v15, v4, v15
	v_cvt_pk_bf16_f32 v28, v5, v15
	v_sub_f32_e32 v5, v30, v31
	v_mov_b32_e32 v30, v75
	v_mov_b32_e32 v31, v67
	v_pk_mul_f32 v[30:31], v[30:31], v[206:207]
	v_mul_f32_e32 v5, v4, v5
	v_sub_f32_e32 v15, v30, v31
	v_mov_b32_e32 v30, v68
	v_mov_b32_e32 v31, v76
	v_pk_mul_f32 v[6:7], v[30:31], v[244:245]
	v_mov_b32_e32 v76, v69
	v_mul_f32_e32 v15, v4, v15
	v_cvt_pk_bf16_f32 v29, v5, v15
	v_add_f32_e32 v5, v7, v6
	v_pk_mul_f32 v[6:7], v[76:77], v[246:247]
	global_load_dwordx4 v[244:247], v[240:241], off offset:48
	v_mov_b32_e32 v8, v70
	v_add_f32_e32 v6, v7, v6
	v_mov_b32_e32 v9, v78
	v_mul_f32_e32 v5, v4, v5
	v_mul_f32_e32 v6, v4, v6
	v_pk_mul_f32 v[8:9], v[8:9], v[248:249]
	v_mov_b32_e32 v78, v71
	v_cvt_pk_bf16_f32 v6, v5, v6
	v_add_f32_e32 v5, v9, v8
	v_pk_mul_f32 v[8:9], v[78:79], v[250:251]
	v_mul_f32_e32 v5, v4, v5
	v_add_f32_e32 v7, v9, v8
	v_mov_b32_e32 v8, v64
	v_mov_b32_e32 v9, v72
	v_mul_f32_e32 v7, v4, v7
	v_pk_mul_f32 v[8:9], v[8:9], v[200:201]
	v_mov_b32_e32 v72, v65
	v_cvt_pk_bf16_f32 v7, v5, v7
	v_add_f32_e32 v5, v9, v8
	v_pk_mul_f32 v[8:9], v[72:73], v[202:203]
	v_mov_b32_e32 v10, v66
	v_add_f32_e32 v8, v9, v8
	v_mov_b32_e32 v11, v74
	v_mul_f32_e32 v5, v4, v5
	v_mul_f32_e32 v8, v4, v8
	v_pk_mul_f32 v[10:11], v[10:11], v[204:205]
	v_mov_b32_e32 v74, v67
	v_cvt_pk_bf16_f32 v8, v5, v8
	v_add_f32_e32 v5, v11, v10
	v_pk_mul_f32 v[10:11], v[74:75], v[206:207]
	v_mul_f32_e32 v5, v4, v5
	v_add_f32_e32 v9, v11, v10
	v_mad_i64_i32 v[10:11], s[0:1], v14, s66, v[0:1]
	v_mul_f32_e32 v9, v4, v9
	v_lshl_add_u64 v[10:11], v[10:11], 0, v[2:3]
	v_add_u32_e32 v14, 0xa0, v16
	v_cvt_pk_bf16_f32 v9, v5, v9
	global_store_dwordx4 v[10:11], v[26:29], off
	v_lshl_add_u64 v[10:11], v[10:11], 0, s[16:17]
	v_ashrrev_i32_e32 v15, 31, v14
	global_store_dwordx4 v[10:11], v[6:9], off
	v_mov_b32_e32 v26, v60
	v_mov_b32_e32 v27, v52
	v_lshlrev_b64 v[6:7], 9, v[14:15]
	v_lshlrev_b64 v[8:9], 8, v[14:15]
	v_lshl_add_u64 v[6:7], s[28:29], 0, v[6:7]
	v_lshl_add_u64 v[8:9], s[12:13], 0, v[8:9]
	v_cndmask_b32_e64 v7, v9, v7, s[6:7]
	v_cndmask_b32_e64 v6, v8, v6, s[6:7]
	v_lshl_add_u64 v[22:23], v[6:7], 0, v[182:183]
	s_nop 0
	v_mov_b32_e32 v28, v62
	v_mov_b32_e32 v29, v54
	v_mov_b32_e32 v30, v58
	v_mov_b32_e32 v31, v50
	s_waitcnt vmcnt(13)
	v_pk_mul_f32 v[26:27], v[26:27], v[208:209]
	s_nop 0
	v_sub_f32_e32 v5, v26, v27
	v_mov_b32_e32 v26, v61
	v_mov_b32_e32 v27, v53
	v_pk_mul_f32 v[26:27], v[26:27], v[210:211]
	v_mul_f32_e32 v5, v4, v5
	v_sub_f32_e32 v15, v26, v27
	s_waitcnt vmcnt(12)
	v_pk_mul_f32 v[28:29], v[28:29], v[212:213]
	v_mul_f32_e32 v15, v4, v15
	v_cvt_pk_bf16_f32 v26, v5, v15
	v_sub_f32_e32 v5, v28, v29
	v_mov_b32_e32 v28, v63
	v_mov_b32_e32 v29, v55
	v_pk_mul_f32 v[28:29], v[28:29], v[214:215]
	v_mul_f32_e32 v5, v4, v5
	v_sub_f32_e32 v15, v28, v29
	v_mov_b32_e32 v28, v56
	v_mov_b32_e32 v29, v48
	s_waitcnt vmcnt(11)
	v_pk_mul_f32 v[28:29], v[28:29], v[216:217]
	v_mul_f32_e32 v15, v4, v15
	v_cvt_pk_bf16_f32 v27, v5, v15
	v_sub_f32_e32 v5, v28, v29
	v_mov_b32_e32 v28, v57
	v_mov_b32_e32 v29, v49
	v_pk_mul_f32 v[28:29], v[28:29], v[218:219]
	v_mul_f32_e32 v5, v4, v5
	v_sub_f32_e32 v15, v28, v29
	s_waitcnt vmcnt(8)
; __device__ __forceinline__ unsigned cvt_pk_bf16(float lo, float hi) { unsigned r; asm volatile("v_cvt_pk_bf16_f32 %0, %1, %2" : "=v"(r) : "v"(lo), "v"(hi)); return r; }
;     __device__ __forceinline__ void operator()(f32x4 (&acc)[2][2][4][2], const pg8::Unit& u, int wr, int wc, int fr, int fq) const {
;     ...
;         if (rope) {
;             const float sc = ((pn < 4) ? SC_QA : (pn >= 9 && pn < 15) ? SC_QB : 1.0f) * ascale;
; #pragma unroll
;             for (int ai = 0; ai < 2; ++ai)
; #pragma unroll
;                 for (int m = 0; m < 4; ++m) {
;                     const int row = row0 + ai * 128 + m * 16;
;                     const f32x4* cp = (md == 1) ? (const f32x4*)(csA + (size_t)row * 32 + 8 * fq) : (const f32x4*)(csB + (size_t)row * 64 + 32 * (wc & 1) + 8 * fq);
;                     const f32x4 t0 = cp[0], t1 = cp[1], t2 = cp[2], t3 = cp[3];
;                     const f32x4 a0 = acc[ai][0][m][0], a1 = acc[ai][0][m][1], b0 = acc[ai][1][m][0], b1 = acc[ai][1][m][1];
;                     u32x4 w0, w1;
;                     w0.x = cvt_pk_bf16((a0[0] * t0[0] - b0[0] * t0[1]) * sc, (a0[1] * t0[2] - b0[1] * t0[3]) * sc);
;                     w0.y = cvt_pk_bf16((a0[2] * t1[0] - b0[2] * t1[1]) * sc, (a0[3] * t1[2] - b0[3] * t1[3]) * sc);
;                     w0.z = cvt_pk_bf16((a1[0] * t2[0] - b1[0] * t2[1]) * sc, (a1[1] * t2[2] - b1[1] * t2[3]) * sc);
;                     w0.w = cvt_pk_bf16((a1[2] * t3[0] - b1[2] * t3[1]) * sc, (a1[3] * t3[2] - b1[3] * t3[3]) * sc);
;                     w1.x = cvt_pk_bf16((b0[0] * t0[0] + a0[0] * t0[1]) * sc, (b0[1] * t0[2] + a0[1] * t0[3]) * sc);
;                     w1.y = cvt_pk_bf16((b0[2] * t1[0] + a0[2] * t1[1]) * sc, (b0[3] * t1[2] + a0[3] * t1[3]) * sc);
;                     w1.z = cvt_pk_bf16((b1[0] * t2[0] + a1[0] * t2[1]) * sc, (b1[1] * t2[2] + a1[1] * t2[3]) * sc);
;                     w1.w = cvt_pk_bf16((b1[2] * t3[0] + a1[2] * t3[1]) * sc, (b1[3] * t3[2] + a1[3] * t3[3]) * sc);
;                     bf16_t* rp = H + (size_t)row * DIN + col0;
;                     *(u32x4*)(rp) = w0; *(u32x4*)(rp + cstep) = w1;
;                     if (m == 3) asm volatile("" ::: "memory");
;                 }
	v_pk_mul_f32 v[30:31], v[30:31], v[220:221]
	v_mul_f32_e32 v15, v4, v15
	v_cvt_pk_bf16_f32 v28, v5, v15
	v_sub_f32_e32 v5, v30, v31
	v_mov_b32_e32 v30, v59
	v_mov_b32_e32 v31, v51
	v_pk_mul_f32 v[30:31], v[30:31], v[222:223]
	v_mul_f32_e32 v5, v4, v5
	v_sub_f32_e32 v15, v30, v31
	v_mov_b32_e32 v30, v52
	v_mov_b32_e32 v31, v60
	v_pk_mul_f32 v[6:7], v[30:31], v[208:209]
	v_mov_b32_e32 v60, v53
	v_mul_f32_e32 v15, v4, v15
	v_cvt_pk_bf16_f32 v29, v5, v15
	v_add_f32_e32 v5, v7, v6
	v_pk_mul_f32 v[6:7], v[60:61], v[210:211]
	v_mov_b32_e32 v8, v54
	v_add_f32_e32 v6, v7, v6
	v_mov_b32_e32 v9, v62
	v_mul_f32_e32 v5, v4, v5
	v_mul_f32_e32 v6, v4, v6
	v_pk_mul_f32 v[8:9], v[8:9], v[212:213]
	v_mov_b32_e32 v62, v55
	v_cvt_pk_bf16_f32 v6, v5, v6
	v_add_f32_e32 v5, v9, v8
	v_pk_mul_f32 v[8:9], v[62:63], v[214:215]
	v_mul_f32_e32 v5, v4, v5
	v_add_f32_e32 v7, v9, v8
	v_mov_b32_e32 v8, v48
	v_mov_b32_e32 v9, v56
	v_mul_f32_e32 v7, v4, v7
	v_pk_mul_f32 v[8:9], v[8:9], v[216:217]
	v_mov_b32_e32 v56, v49
	v_cvt_pk_bf16_f32 v7, v5, v7
	v_add_f32_e32 v5, v9, v8
	v_pk_mul_f32 v[8:9], v[56:57], v[218:219]
	v_mov_b32_e32 v10, v50
	v_add_f32_e32 v8, v9, v8
	v_mov_b32_e32 v11, v58
	v_mul_f32_e32 v5, v4, v5
	v_mul_f32_e32 v8, v4, v8
	v_pk_mul_f32 v[10:11], v[10:11], v[220:221]
	v_mov_b32_e32 v58, v51
	v_cvt_pk_bf16_f32 v8, v5, v8
	v_add_f32_e32 v5, v11, v10
	v_pk_mul_f32 v[10:11], v[58:59], v[222:223]
	v_mul_f32_e32 v5, v4, v5
	v_add_f32_e32 v9, v11, v10
	v_mad_i64_i32 v[10:11], s[0:1], v14, s66, v[0:1]
	v_mul_f32_e32 v9, v4, v9
	v_lshl_add_u64 v[10:11], v[10:11], 0, v[2:3]
	v_cvt_pk_bf16_f32 v9, v5, v9
	global_store_dwordx4 v[10:11], v[26:29], off
	v_lshl_add_u64 v[10:11], v[10:11], 0, s[16:17]
	global_store_dwordx4 v[10:11], v[6:9], off
	v_add_u32_e32 v26, 0xb0, v16
	v_ashrrev_i32_e32 v27, 31, v26
	v_lshlrev_b64 v[6:7], 9, v[26:27]
	v_lshlrev_b64 v[8:9], 8, v[26:27]
	v_lshl_add_u64 v[6:7], s[28:29], 0, v[6:7]
	v_lshl_add_u64 v[8:9], s[12:13], 0, v[8:9]
	v_cndmask_b32_e64 v7, v9, v7, s[6:7]
	v_cndmask_b32_e64 v6, v8, v6, s[6:7]
	v_lshl_add_u64 v[18:19], v[6:7], 0, v[182:183]
	s_nop 0
	v_mov_b32_e32 v22, v44
	v_mov_b32_e32 v23, v36
	v_mov_b32_e32 v24, v46
	v_mov_b32_e32 v25, v38
	v_mov_b32_e32 v28, v42
	v_mov_b32_e32 v29, v34
	v_mad_i64_i32 v[0:1], s[0:1], v26, s66, v[0:1]
	v_lshl_add_u64 v[0:1], v[0:1], 0, v[2:3]
	s_waitcnt vmcnt(9)
	v_pk_mul_f32 v[22:23], v[22:23], v[224:225]
	s_nop 0
	v_sub_f32_e32 v5, v22, v23
	v_mov_b32_e32 v22, v45
	v_mov_b32_e32 v23, v37
	v_pk_mul_f32 v[22:23], v[22:23], v[226:227]
	v_mul_f32_e32 v5, v4, v5
	v_sub_f32_e32 v22, v22, v23
	v_mul_f32_e32 v22, v4, v22
	s_waitcnt vmcnt(8)
	v_pk_mul_f32 v[24:25], v[24:25], v[228:229]
	v_cvt_pk_bf16_f32 v22, v5, v22
	s_waitcnt vmcnt(4)
	v_pk_mul_f32 v[28:29], v[28:29], v[244:245]
	v_sub_f32_e32 v5, v24, v25
	v_mov_b32_e32 v24, v47
	v_mov_b32_e32 v25, v39
	v_pk_mul_f32 v[24:25], v[24:25], v[230:231]
	v_mul_f32_e32 v5, v4, v5
	v_sub_f32_e32 v23, v24, v25
	v_mov_b32_e32 v24, v40
	v_mov_b32_e32 v25, v32
	v_mul_f32_e32 v23, v4, v23
	v_pk_mul_f32 v[24:25], v[24:25], v[236:237]
	v_cvt_pk_bf16_f32 v23, v5, v23
	s_nop 0
	v_sub_f32_e32 v5, v24, v25
	v_mov_b32_e32 v24, v41
	v_mov_b32_e32 v25, v33
	v_pk_mul_f32 v[24:25], v[24:25], v[238:239]
	v_mul_f32_e32 v5, v4, v5
	v_sub_f32_e32 v24, v24, v25
	v_mul_f32_e32 v24, v4, v24
	v_cvt_pk_bf16_f32 v24, v5, v24
	v_sub_f32_e32 v5, v28, v29
	v_mov_b32_e32 v28, v43
	v_mov_b32_e32 v29, v35
	v_pk_mul_f32 v[28:29], v[28:29], v[246:247]
	v_mul_f32_e32 v5, v4, v5
	v_sub_f32_e32 v25, v28, v29
	v_mov_b32_e32 v28, v36
	v_mov_b32_e32 v29, v44
	v_mul_f32_e32 v25, v4, v25
	v_pk_mul_f32 v[6:7], v[28:29], v[224:225]
	v_mov_b32_e32 v44, v37
	v_cvt_pk_bf16_f32 v25, v5, v25
	v_add_f32_e32 v5, v7, v6
	v_pk_mul_f32 v[6:7], v[44:45], v[226:227]
	v_mov_b32_e32 v8, v38
	v_add_f32_e32 v6, v7, v6
	v_mov_b32_e32 v9, v46
	v_mul_f32_e32 v5, v4, v5
	v_mul_f32_e32 v6, v4, v6
	v_pk_mul_f32 v[8:9], v[8:9], v[228:229]
	v_mov_b32_e32 v46, v39
	v_cvt_pk_bf16_f32 v6, v5, v6
	v_add_f32_e32 v5, v9, v8
	v_pk_mul_f32 v[8:9], v[46:47], v[230:231]
	v_mul_f32_e32 v5, v4, v5
	v_add_f32_e32 v7, v9, v8
	v_mov_b32_e32 v8, v32
	v_mov_b32_e32 v9, v40
	v_mul_f32_e32 v7, v4, v7
	v_pk_mul_f32 v[8:9], v[8:9], v[236:237]
	v_mov_b32_e32 v40, v33
	v_cvt_pk_bf16_f32 v7, v5, v7
	v_add_f32_e32 v5, v9, v8
	v_pk_mul_f32 v[8:9], v[40:41], v[238:239]
	v_mov_b32_e32 v10, v34
	v_add_f32_e32 v8, v9, v8
	v_mov_b32_e32 v11, v42
	v_mul_f32_e32 v5, v4, v5
	v_mul_f32_e32 v8, v4, v8
	v_pk_mul_f32 v[10:11], v[10:11], v[244:245]
	v_mov_b32_e32 v42, v35
	v_cvt_pk_bf16_f32 v8, v5, v8
	v_add_f32_e32 v5, v11, v10
	v_pk_mul_f32 v[10:11], v[42:43], v[246:247]
	v_mul_f32_e32 v5, v4, v5
	v_add_f32_e32 v9, v11, v10
	v_mul_f32_e32 v4, v4, v9
	v_cvt_pk_bf16_f32 v9, v5, v4
	global_store_dwordx4 v[0:1], v[22:25], off
	v_lshl_add_u64 v[0:1], v[0:1], 0, s[16:17]
	global_store_dwordx4 v[0:1], v[6:9], off
	s_andn2_b64 vcc, exec, s[4:5]
	s_mov_b64 s[0:1], -1
	s_cbranch_vccnz .LBB0_70
